# v43 + GEMM main loop: address add moved into the M0 wait-state slot before each second LDS-DMA load, 9 s_nop 0 removed (m0 staged through vcc_lo where s30 was reused)
# baseline (speedup 1.0000x reference)
; #define LDA(dst, b, h) _Pragma("unroll") for (int m = 0; m < 4; ++m) _Pragma("unroll") for (int k = 0; k < 2; ++k) \
;     dst[m][k] = *reinterpret_cast<const bf16x8*>((char*)SA(b, h) + lds_byte(wr * 64 + m * 16 + fr, k * 32 + fq * 8))
; #define LDB(dst, b, h) _Pragma("unroll") for (int n = 0; n < 2; ++n) _Pragma("unroll") for (int k = 0; k < 2; ++k) \
;     dst[n][k] = *reinterpret_cast<const bf16x8*>((char*)SB(b, h) + lds_byte(wc * 32 + n * 16 + fr, k * 32 + fq * 8))
; #define MMA(ai, bj, At_, Bt_) do { __builtin_amdgcn_s_setprio(1); \
;     _Pragma("unroll") for (int m = 0; m < 4; ++m) _Pragma("unroll") for (int n = 0; n < 2; ++n) _Pragma("unroll") for (int k = 0; k < 2; ++k) \
;       acc[ai][bj][m][n] = __builtin_amdgcn_mfma_f32_16x16x32_bf16(Bt_[n][k], At_[m][k], acc[ai][bj][m][n], 0, 0, 0); \
;     __builtin_amdgcn_s_setprio(0); } while (0)
; #define WAIT_V(n) asm volatile("s_waitcnt vmcnt(" #n ")" ::: "memory")
; #define WAIT_L(n) asm volatile("s_waitcnt lgkmcnt(" #n ")" ::: "memory")
; #define BAR __builtin_amdgcn_s_barrier()
; #define SCHED __builtin_amdgcn_sched_barrier(0)
; __device__ __forceinline__ void gemm_tile(const TileDesc& td, unsigned char* lds) {
;     ...
;     for (int t = 0; t < nt - 2; t += 2) {
;         LDB(B0, 0, 0); SCHED; LDA(At, 0, 0); STAGE(SA(1, 1), A, lda, brow + HALF, t + 1);
;         WAIT_L(8); BAR; WAIT_L(0); MMA(0, 0, At, B0); BAR; SCHED;
;         LDB(B1, 0, 1); STAGE(SB(0, 0), Bt, ldb, bcol, t + 2);
;         BAR; WAIT_L(0); MMA(0, 1, At, B1); BAR;
;         LDA(At, 0, 1); STAGE(SA(0, 0), A, lda, brow, t + 2);
;         BAR; WAIT_L(0); MMA(1, 0, At, B0); BAR; SCHED;
;         STAGE(SB(0, 1), Bt, ldb, bcol + HALF, t + 2);
;         WAIT_V(6); BAR; MMA(1, 1, At, B1); BAR;
.LBB0_247:
	ds_read_b128 v[190:193], v183
	ds_read_b128 v[194:197], v183 offset:1024
	ds_read_b128 v[198:201], v183 offset:2048
	ds_read_b128 v[202:205], v183 offset:3072
	s_add_u32 s7, s4, s78
	s_addc_u32 s62, s5, s79
	s_add_u32 s30, s7, 0x80
	v_add_u32_e32 v162, 0xc000, v139
	s_addc_u32 s31, s62, 0
	v_readfirstlane_b32 s63, v162
	v_add_u32_e32 v252, v182, v154
	v_lshl_add_u64 v[160:161], s[30:31], 0, v[128:129]
	s_mov_b32 m0, s63
	v_add_u32_e32 v162, 0xe000, v139
	ds_read_b128 v[206:209], v252
	ds_read_b128 v[210:213], v252 offset:1024
	ds_read_b128 v[214:217], v184
	ds_read_b128 v[218:221], v184 offset:1024
	ds_read_b128 v[222:225], v185
	ds_read_b128 v[226:229], v185 offset:1024
	ds_read_b128 v[230:233], v186
	ds_read_b128 v[234:237], v186 offset:1024
	global_load_lds_dwordx4 v[160:161], off
	v_readfirstlane_b32 vcc_lo, v162
	s_mov_b32 m0, vcc_lo
	v_lshl_add_u64 v[160:161], s[30:31], 0, v[130:131]
	global_load_lds_dwordx4 v[160:161], off
	s_waitcnt lgkmcnt(8)
	s_barrier
	s_waitcnt lgkmcnt(0)
	v_mfma_f32_16x16x32_bf16 v[100:103], v[190:193], v[206:209], v[100:103]
	v_mfma_f32_16x16x32_bf16 v[124:127], v[198:201], v[206:209], v[124:127]
	v_mfma_f32_16x16x32_bf16 v[120:123], v[190:193], v[214:217], v[120:123]
	v_mfma_f32_16x16x32_bf16 v[116:119], v[198:201], v[214:217], v[116:119]
	v_mfma_f32_16x16x32_bf16 v[112:115], v[190:193], v[222:225], v[112:115]
	v_mfma_f32_16x16x32_bf16 v[108:111], v[198:201], v[222:225], v[108:111]
	v_mfma_f32_16x16x32_bf16 v[104:107], v[190:193], v[230:233], v[104:107]
	v_mfma_f32_16x16x32_bf16 v[96:99], v[198:201], v[230:233], v[96:99]
	v_mfma_f32_16x16x32_bf16 v[100:103], v[194:197], v[210:213], v[100:103]
	v_mfma_f32_16x16x32_bf16 v[124:127], v[202:205], v[210:213], v[124:127]
	v_mfma_f32_16x16x32_bf16 v[120:123], v[194:197], v[218:221], v[120:123]
	v_mfma_f32_16x16x32_bf16 v[116:119], v[202:205], v[218:221], v[116:119]
	v_mfma_f32_16x16x32_bf16 v[112:115], v[194:197], v[226:229], v[112:115]
	v_mfma_f32_16x16x32_bf16 v[108:111], v[202:205], v[226:229], v[108:111]
	v_mfma_f32_16x16x32_bf16 v[104:107], v[194:197], v[234:237], v[104:107]
	v_mfma_f32_16x16x32_bf16 v[96:99], v[202:205], v[234:237], v[96:99]
	s_barrier
	s_add_i32 s3, s3, 2
	s_add_u32 s63, s18, s78
	s_addc_u32 s65, s19, s79
	s_add_u32 s30, s63, 0x100
	s_addc_u32 s31, s65, 0
	v_readfirstlane_b32 s66, v152
	v_lshl_add_u64 v[168:169], s[30:31], 0, v[132:133]
	s_mov_b32 m0, s66
	ds_read_b128 v[238:241], v187
	ds_read_b128 v[242:245], v187 offset:1024
	ds_read_b128 v[246:249], v187 offset:2048
	ds_read_b128 v[160:163], v187 offset:3072
	global_load_lds_dwordx4 v[168:169], off
	v_readfirstlane_b32 vcc_lo, v153
	s_mov_b32 m0, vcc_lo
	v_lshl_add_u64 v[168:169], s[30:31], 0, v[136:137]
	global_load_lds_dwordx4 v[168:169], off
	s_barrier
	s_waitcnt lgkmcnt(0)
	v_mfma_f32_16x16x32_bf16 v[92:95], v[238:241], v[206:209], v[92:95]
	v_mfma_f32_16x16x32_bf16 v[88:91], v[246:249], v[206:209], v[88:91]
	v_mfma_f32_16x16x32_bf16 v[84:87], v[238:241], v[214:217], v[84:87]
	v_mfma_f32_16x16x32_bf16 v[80:83], v[246:249], v[214:217], v[80:83]
	v_mfma_f32_16x16x32_bf16 v[76:79], v[238:241], v[222:225], v[76:79]
	v_mfma_f32_16x16x32_bf16 v[72:75], v[246:249], v[222:225], v[72:75]
	v_mfma_f32_16x16x32_bf16 v[68:71], v[238:241], v[230:233], v[68:71]
	v_mfma_f32_16x16x32_bf16 v[64:67], v[246:249], v[230:233], v[64:67]
	v_mfma_f32_16x16x32_bf16 v[92:95], v[242:245], v[210:213], v[92:95]
	v_mfma_f32_16x16x32_bf16 v[88:91], v[160:163], v[210:213], v[88:91]
	v_mfma_f32_16x16x32_bf16 v[84:87], v[242:245], v[218:221], v[84:87]
	v_mfma_f32_16x16x32_bf16 v[80:83], v[160:163], v[218:221], v[80:83]
	v_mfma_f32_16x16x32_bf16 v[76:79], v[242:245], v[226:229], v[76:79]
	v_mfma_f32_16x16x32_bf16 v[72:75], v[160:163], v[226:229], v[72:75]
	v_mfma_f32_16x16x32_bf16 v[68:71], v[242:245], v[234:237], v[68:71]
	v_mfma_f32_16x16x32_bf16 v[64:67], v[160:163], v[234:237], v[64:67]
	s_add_u32 s66, s24, s78
	s_addc_u32 s67, s25, s79
	s_add_u32 s30, s66, 0x100
	s_addc_u32 s31, s67, 0
	v_readfirstlane_b32 s70, v139
	v_lshl_add_u64 v[168:169], s[30:31], 0, v[128:129]
	s_mov_b32 m0, s70
	s_barrier
	ds_read_b128 v[206:209], v252 offset:16384
	ds_read_b128 v[210:213], v252 offset:17408
	ds_read_b128 v[214:217], v184 offset:16384
	ds_read_b128 v[218:221], v184 offset:17408
	ds_read_b128 v[222:225], v185 offset:16384
	ds_read_b128 v[226:229], v185 offset:17408
	ds_read_b128 v[230:233], v186 offset:16384
	ds_read_b128 v[234:237], v186 offset:17408
	global_load_lds_dwordx4 v[168:169], off
	v_readfirstlane_b32 vcc_lo, v155
	s_mov_b32 m0, vcc_lo
	v_lshl_add_u64 v[168:169], s[30:31], 0, v[130:131]
	global_load_lds_dwordx4 v[168:169], off
	s_barrier
	s_waitcnt lgkmcnt(0)
	v_mfma_f32_16x16x32_bf16 v[60:63], v[190:193], v[206:209], v[60:63]
	v_mfma_f32_16x16x32_bf16 v[56:59], v[198:201], v[206:209], v[56:59]
	v_mfma_f32_16x16x32_bf16 v[52:55], v[190:193], v[214:217], v[52:55]
	v_mfma_f32_16x16x32_bf16 v[48:51], v[198:201], v[214:217], v[48:51]
	v_mfma_f32_16x16x32_bf16 v[44:47], v[190:193], v[222:225], v[44:47]
	v_mfma_f32_16x16x32_bf16 v[40:43], v[198:201], v[222:225], v[40:43]
	v_mfma_f32_16x16x32_bf16 v[36:39], v[190:193], v[230:233], v[36:39]
	v_mfma_f32_16x16x32_bf16 v[32:35], v[198:201], v[230:233], v[32:35]
	v_mfma_f32_16x16x32_bf16 v[60:63], v[194:197], v[210:213], v[60:63]
	v_mfma_f32_16x16x32_bf16 v[56:59], v[202:205], v[210:213], v[56:59]
	v_mfma_f32_16x16x32_bf16 v[52:55], v[194:197], v[218:221], v[52:55]
	v_mfma_f32_16x16x32_bf16 v[48:51], v[202:205], v[218:221], v[48:51]
	v_mfma_f32_16x16x32_bf16 v[44:47], v[194:197], v[226:229], v[44:47]
	v_mfma_f32_16x16x32_bf16 v[40:43], v[202:205], v[226:229], v[40:43]
	v_mfma_f32_16x16x32_bf16 v[36:39], v[194:197], v[234:237], v[36:39]
	v_mfma_f32_16x16x32_bf16 v[32:35], v[202:205], v[234:237], v[32:35]
	s_barrier
; #define LDA(dst, b, h) _Pragma("unroll") for (int m = 0; m < 4; ++m) _Pragma("unroll") for (int k = 0; k < 2; ++k) \
;     dst[m][k] = *reinterpret_cast<const bf16x8*>((char*)SA(b, h) + lds_byte(wr * 64 + m * 16 + fr, k * 32 + fq * 8))
; #define LDB(dst, b, h) _Pragma("unroll") for (int n = 0; n < 2; ++n) _Pragma("unroll") for (int k = 0; k < 2; ++k) \
;     dst[n][k] = *reinterpret_cast<const bf16x8*>((char*)SB(b, h) + lds_byte(wc * 32 + n * 16 + fr, k * 32 + fq * 8))
; #define MMA(ai, bj, At_, Bt_) do { __builtin_amdgcn_s_setprio(1); \
;     _Pragma("unroll") for (int m = 0; m < 4; ++m) _Pragma("unroll") for (int n = 0; n < 2; ++n) _Pragma("unroll") for (int k = 0; k < 2; ++k) \
;       acc[ai][bj][m][n] = __builtin_amdgcn_mfma_f32_16x16x32_bf16(Bt_[n][k], At_[m][k], acc[ai][bj][m][n], 0, 0, 0); \
;     __builtin_amdgcn_s_setprio(0); } while (0)
; #define WAIT_V(n) asm volatile("s_waitcnt vmcnt(" #n ")" ::: "memory")
; #define WAIT_L(n) asm volatile("s_waitcnt lgkmcnt(" #n ")" ::: "memory")
; #define BAR __builtin_amdgcn_s_barrier()
; #define SCHED __builtin_amdgcn_sched_barrier(0)
; __device__ __forceinline__ void gemm_tile(const TileDesc& td, unsigned char* lds) {
;     ...
;         STAGE(SB(0, 1), Bt, ldb, bcol + HALF, t + 2);
;         WAIT_V(6); BAR; MMA(1, 1, At, B1); BAR;
;         LDB(B0, 1, 0); SCHED; LDA(At, 1, 0); STAGE(SA(0, 1), A, lda, brow + HALF, t + 2);
;         WAIT_L(8); BAR; WAIT_L(0); MMA(0, 0, At, B0); BAR; SCHED;
;         LDB(B1, 1, 1); STAGE(SB(1, 0), Bt, ldb, bcol, t + 3);
;         BAR; WAIT_L(0); MMA(0, 1, At, B1); BAR;
;         LDA(At, 1, 1); STAGE(SA(1, 0), A, lda, brow, t + 3);
	s_add_u32 s70, s80, s78
	s_addc_u32 s88, s81, s79
	s_add_u32 s30, s70, 0x100
	s_addc_u32 s31, s88, 0
	v_readfirstlane_b32 s89, v156
	s_mov_b32 m0, s89
	v_lshl_add_u64 v[168:169], s[30:31], 0, v[132:133]
	global_load_lds_dwordx4 v[168:169], off
	v_readfirstlane_b32 vcc_lo, v157
	s_mov_b32 m0, vcc_lo
	v_lshl_add_u64 v[168:169], s[30:31], 0, v[136:137]
	global_load_lds_dwordx4 v[168:169], off
	s_waitcnt vmcnt(6)
	s_barrier
	v_mfma_f32_16x16x32_bf16 v[28:31], v[238:241], v[206:209], v[28:31]
	v_mfma_f32_16x16x32_bf16 v[24:27], v[246:249], v[206:209], v[24:27]
	v_mfma_f32_16x16x32_bf16 v[20:23], v[238:241], v[214:217], v[20:23]
	v_mfma_f32_16x16x32_bf16 v[16:19], v[246:249], v[214:217], v[16:19]
	v_mfma_f32_16x16x32_bf16 v[12:15], v[238:241], v[222:225], v[12:15]
	v_mfma_f32_16x16x32_bf16 v[8:11], v[246:249], v[222:225], v[8:11]
	v_mfma_f32_16x16x32_bf16 v[4:7], v[238:241], v[230:233], v[4:7]
	v_mfma_f32_16x16x32_bf16 v[0:3], v[246:249], v[230:233], v[0:3]
	v_mfma_f32_16x16x32_bf16 v[28:31], v[242:245], v[210:213], v[28:31]
	v_mfma_f32_16x16x32_bf16 v[24:27], v[160:163], v[210:213], v[24:27]
	v_mfma_f32_16x16x32_bf16 v[20:23], v[242:245], v[218:221], v[20:23]
	v_mfma_f32_16x16x32_bf16 v[16:19], v[160:163], v[218:221], v[16:19]
	v_mfma_f32_16x16x32_bf16 v[12:15], v[242:245], v[226:229], v[12:15]
	v_mfma_f32_16x16x32_bf16 v[8:11], v[160:163], v[226:229], v[8:11]
	v_mfma_f32_16x16x32_bf16 v[4:7], v[242:245], v[234:237], v[4:7]
	v_mfma_f32_16x16x32_bf16 v[0:3], v[160:163], v[234:237], v[0:3]
	s_barrier
	ds_read_b128 v[160:163], v188
	ds_read_b128 v[190:193], v188 offset:1024
	ds_read_b128 v[194:197], v188 offset:2048
	ds_read_b128 v[198:201], v188 offset:3072
	s_add_u32 s30, s7, 0x100
	s_addc_u32 s31, s62, 0
	v_readfirstlane_b32 s7, v174
	v_lshl_add_u64 v[168:169], s[30:31], 0, v[128:129]
	s_mov_b32 m0, s7
	v_readfirstlane_b32 s7, v175
	ds_read_b128 v[202:205], v252 offset:32768
	ds_read_b128 v[206:209], v252 offset:33792
	ds_read_b128 v[210:213], v184 offset:32768
	ds_read_b128 v[214:217], v184 offset:33792
	ds_read_b128 v[218:221], v185 offset:32768
	ds_read_b128 v[222:225], v185 offset:33792
	ds_read_b128 v[226:229], v186 offset:32768
	ds_read_b128 v[230:233], v186 offset:33792
	global_load_lds_dwordx4 v[168:169], off
	s_mov_b32 m0, s7
	v_lshl_add_u64 v[168:169], s[30:31], 0, v[130:131]
	global_load_lds_dwordx4 v[168:169], off
	s_waitcnt lgkmcnt(8)
	s_barrier
	s_waitcnt lgkmcnt(0)
	v_mfma_f32_16x16x32_bf16 v[100:103], v[160:163], v[202:205], v[100:103]
	v_mfma_f32_16x16x32_bf16 v[124:127], v[194:197], v[202:205], v[124:127]
	v_mfma_f32_16x16x32_bf16 v[120:123], v[160:163], v[210:213], v[120:123]
	v_mfma_f32_16x16x32_bf16 v[116:119], v[194:197], v[210:213], v[116:119]
	v_mfma_f32_16x16x32_bf16 v[112:115], v[160:163], v[218:221], v[112:115]
	v_mfma_f32_16x16x32_bf16 v[108:111], v[194:197], v[218:221], v[108:111]
	v_mfma_f32_16x16x32_bf16 v[104:107], v[160:163], v[226:229], v[104:107]
	v_mfma_f32_16x16x32_bf16 v[96:99], v[194:197], v[226:229], v[96:99]
	v_mfma_f32_16x16x32_bf16 v[100:103], v[190:193], v[206:209], v[100:103]
	v_mfma_f32_16x16x32_bf16 v[124:127], v[198:201], v[206:209], v[124:127]
	v_mfma_f32_16x16x32_bf16 v[120:123], v[190:193], v[214:217], v[120:123]
	v_mfma_f32_16x16x32_bf16 v[116:119], v[198:201], v[214:217], v[116:119]
	v_mfma_f32_16x16x32_bf16 v[112:115], v[190:193], v[222:225], v[112:115]
	v_mfma_f32_16x16x32_bf16 v[108:111], v[198:201], v[222:225], v[108:111]
	v_mfma_f32_16x16x32_bf16 v[104:107], v[190:193], v[230:233], v[104:107]
	v_mfma_f32_16x16x32_bf16 v[96:99], v[198:201], v[230:233], v[96:99]
	s_barrier
	s_add_u32 s30, s63, 0x180
	s_addc_u32 s31, s65, 0
	v_readfirstlane_b32 s7, v176
	v_lshl_add_u64 v[168:169], s[30:31], 0, v[132:133]
	s_mov_b32 m0, s7
	v_readfirstlane_b32 s7, v177
	ds_read_b128 v[234:237], v189
	ds_read_b128 v[238:241], v189 offset:1024
	ds_read_b128 v[242:245], v189 offset:2048
	ds_read_b128 v[246:249], v189 offset:3072
	global_load_lds_dwordx4 v[168:169], off
	s_mov_b32 m0, s7
	v_lshl_add_u64 v[168:169], s[30:31], 0, v[136:137]
	global_load_lds_dwordx4 v[168:169], off
	s_barrier
; #define LDA(dst, b, h) _Pragma("unroll") for (int m = 0; m < 4; ++m) _Pragma("unroll") for (int k = 0; k < 2; ++k) \
;     dst[m][k] = *reinterpret_cast<const bf16x8*>((char*)SA(b, h) + lds_byte(wr * 64 + m * 16 + fr, k * 32 + fq * 8))
; #define MMA(ai, bj, At_, Bt_) do { __builtin_amdgcn_s_setprio(1); \
;     _Pragma("unroll") for (int m = 0; m < 4; ++m) _Pragma("unroll") for (int n = 0; n < 2; ++n) _Pragma("unroll") for (int k = 0; k < 2; ++k) \
;       acc[ai][bj][m][n] = __builtin_amdgcn_mfma_f32_16x16x32_bf16(Bt_[n][k], At_[m][k], acc[ai][bj][m][n], 0, 0, 0); \
;     __builtin_amdgcn_s_setprio(0); } while (0)
; #define WAIT_V(n) asm volatile("s_waitcnt vmcnt(" #n ")" ::: "memory")
; #define WAIT_L(n) asm volatile("s_waitcnt lgkmcnt(" #n ")" ::: "memory")
; #define BAR __builtin_amdgcn_s_barrier()
; #define SCHED __builtin_amdgcn_sched_barrier(0)
; __device__ __forceinline__ void gemm_tile(const TileDesc& td, unsigned char* lds) {
;     ...
;         LDA(At, 1, 1); STAGE(SA(1, 0), A, lda, brow, t + 3);
;         BAR; WAIT_L(0); MMA(1, 0, At, B0); BAR; SCHED;
;         STAGE(SB(1, 1), Bt, ldb, bcol + HALF, t + 3);
;         WAIT_V(6); BAR; MMA(1, 1, At, B1); BAR;
;     }
	s_waitcnt lgkmcnt(0)
	v_mfma_f32_16x16x32_bf16 v[92:95], v[234:237], v[202:205], v[92:95]
	v_mfma_f32_16x16x32_bf16 v[88:91], v[242:245], v[202:205], v[88:91]
	v_mfma_f32_16x16x32_bf16 v[84:87], v[234:237], v[210:213], v[84:87]
	v_mfma_f32_16x16x32_bf16 v[80:83], v[242:245], v[210:213], v[80:83]
	v_mfma_f32_16x16x32_bf16 v[76:79], v[234:237], v[218:221], v[76:79]
	v_mfma_f32_16x16x32_bf16 v[72:75], v[242:245], v[218:221], v[72:75]
	v_mfma_f32_16x16x32_bf16 v[68:71], v[234:237], v[226:229], v[68:71]
	v_mfma_f32_16x16x32_bf16 v[64:67], v[242:245], v[226:229], v[64:67]
	v_mfma_f32_16x16x32_bf16 v[92:95], v[238:241], v[206:209], v[92:95]
	v_mfma_f32_16x16x32_bf16 v[88:91], v[246:249], v[206:209], v[88:91]
	v_mfma_f32_16x16x32_bf16 v[84:87], v[238:241], v[214:217], v[84:87]
	v_mfma_f32_16x16x32_bf16 v[80:83], v[246:249], v[214:217], v[80:83]
	v_mfma_f32_16x16x32_bf16 v[76:79], v[238:241], v[222:225], v[76:79]
	v_mfma_f32_16x16x32_bf16 v[72:75], v[246:249], v[222:225], v[72:75]
	v_mfma_f32_16x16x32_bf16 v[68:71], v[238:241], v[230:233], v[68:71]
	v_mfma_f32_16x16x32_bf16 v[64:67], v[246:249], v[230:233], v[64:67]
	s_add_u32 s30, s66, 0x180
	s_addc_u32 s31, s67, 0
	v_readfirstlane_b32 s7, v178
	v_lshl_add_u64 v[168:169], s[30:31], 0, v[128:129]
	s_mov_b32 m0, s7
	v_readfirstlane_b32 s7, v179
	s_barrier
	ds_read_b128 v[202:205], v252 offset:49152
	ds_read_b128 v[206:209], v252 offset:50176
	ds_read_b128 v[210:213], v184 offset:49152
	ds_read_b128 v[214:217], v184 offset:50176
	ds_read_b128 v[218:221], v185 offset:49152
	ds_read_b128 v[222:225], v185 offset:50176
	ds_read_b128 v[226:229], v186 offset:49152
	ds_read_b128 v[230:233], v186 offset:50176
	global_load_lds_dwordx4 v[168:169], off
	s_mov_b32 m0, s7
	v_lshl_add_u64 v[168:169], s[30:31], 0, v[130:131]
	global_load_lds_dwordx4 v[168:169], off
	s_barrier
	s_waitcnt lgkmcnt(0)
	v_mfma_f32_16x16x32_bf16 v[60:63], v[160:163], v[202:205], v[60:63]
	v_mfma_f32_16x16x32_bf16 v[56:59], v[194:197], v[202:205], v[56:59]
	v_mfma_f32_16x16x32_bf16 v[52:55], v[160:163], v[210:213], v[52:55]
	v_mfma_f32_16x16x32_bf16 v[48:51], v[194:197], v[210:213], v[48:51]
	v_mfma_f32_16x16x32_bf16 v[44:47], v[160:163], v[218:221], v[44:47]
	v_mfma_f32_16x16x32_bf16 v[40:43], v[194:197], v[218:221], v[40:43]
	v_mfma_f32_16x16x32_bf16 v[36:39], v[160:163], v[226:229], v[36:39]
	v_mfma_f32_16x16x32_bf16 v[32:35], v[194:197], v[226:229], v[32:35]
	v_mfma_f32_16x16x32_bf16 v[60:63], v[190:193], v[206:209], v[60:63]
	v_mfma_f32_16x16x32_bf16 v[56:59], v[198:201], v[206:209], v[56:59]
	v_mfma_f32_16x16x32_bf16 v[52:55], v[190:193], v[214:217], v[52:55]
	v_mfma_f32_16x16x32_bf16 v[48:51], v[198:201], v[214:217], v[48:51]
	v_mfma_f32_16x16x32_bf16 v[44:47], v[190:193], v[222:225], v[44:47]
	v_mfma_f32_16x16x32_bf16 v[40:43], v[198:201], v[222:225], v[40:43]
	v_mfma_f32_16x16x32_bf16 v[36:39], v[190:193], v[230:233], v[36:39]
	v_mfma_f32_16x16x32_bf16 v[32:35], v[198:201], v[230:233], v[32:35]
	s_barrier
	s_add_u32 s30, s70, 0x180
	s_addc_u32 s31, s88, 0
	v_readfirstlane_b32 s7, v180
	v_lshl_add_u64 v[160:161], s[30:31], 0, v[132:133]
	s_mov_b32 m0, s7
	v_readfirstlane_b32 s7, v181
	global_load_lds_dwordx4 v[160:161], off
	s_mov_b32 m0, s7
	v_lshl_add_u64 v[160:161], s[30:31], 0, v[136:137]
	global_load_lds_dwordx4 v[160:161], off
	s_waitcnt vmcnt(6)
	s_barrier
	v_mfma_f32_16x16x32_bf16 v[28:31], v[234:237], v[202:205], v[28:31]
	v_mfma_f32_16x16x32_bf16 v[24:27], v[242:245], v[202:205], v[24:27]
	v_mfma_f32_16x16x32_bf16 v[20:23], v[234:237], v[210:213], v[20:23]
	v_mfma_f32_16x16x32_bf16 v[16:19], v[242:245], v[210:213], v[16:19]
	v_mfma_f32_16x16x32_bf16 v[12:15], v[234:237], v[218:221], v[12:15]
	v_mfma_f32_16x16x32_bf16 v[8:11], v[242:245], v[218:221], v[8:11]
	v_mfma_f32_16x16x32_bf16 v[4:7], v[234:237], v[226:229], v[4:7]
	v_mfma_f32_16x16x32_bf16 v[0:3], v[242:245], v[226:229], v[0:3]
	v_mfma_f32_16x16x32_bf16 v[28:31], v[238:241], v[206:209], v[28:31]
	v_mfma_f32_16x16x32_bf16 v[24:27], v[246:249], v[206:209], v[24:27]
	v_mfma_f32_16x16x32_bf16 v[20:23], v[238:241], v[214:217], v[20:23]
	v_mfma_f32_16x16x32_bf16 v[16:19], v[246:249], v[214:217], v[16:19]
	v_mfma_f32_16x16x32_bf16 v[12:15], v[238:241], v[222:225], v[12:15]
	v_mfma_f32_16x16x32_bf16 v[8:11], v[246:249], v[222:225], v[8:11]
	v_mfma_f32_16x16x32_bf16 v[4:7], v[238:241], v[230:233], v[4:7]
	v_mfma_f32_16x16x32_bf16 v[0:3], v[246:249], v[230:233], v[0:3]
	s_add_u32 s78, s78, 0x100
	s_addc_u32 s79, s79, 0
	s_cmp_lt_i32 s3, s2
	s_barrier
	s_cbranch_scc1 .LBB0_247
	v_or_b32_e32 v182, 0x400, v138
	v_or_b32_e32 v183, 0x800, v138
	v_or_b32_e32 v184, 0xc00, v138
	v_mov_b32_e32 v185, v154
	v_mov_b32_e32 v235, v159
	v_mov_b32_e32 v236, v172
	v_mov_b32_e32 v172, v170
	v_mov_b32_e32 v170, v173
	v_mov_b32_e32 v237, v165
	v_mov_b32_e32 v165, v167
	v_mov_b32_e32 v238, v135
	v_mov_b32_e32 v135, v171
	v_mov_b32_e32 v167, 0x42000000
